# chunkB loop: P and Rh operand blocks loaded once per workgroup and staged in LDS (no per-wave fragment loads or rotations)
# baseline (speedup 1.0000x reference)
; #define LAS __attribute__((address_space(3)))
; __device__ __forceinline__ void chunkB_item(const Args& A, LAS unsigned char* lds, int tid, int lane, int wave, int bh) {
;     const int fr = lane & 15, q4 = lane >> 4, mt = wave >> 1, nt0 = (wave & 1) * 2, v0 = mt * 16 + q4 * 4;
;     const int h = bh & 7, b = bh >> 3, colg = h * 64 + v0;
;     const bf16_t* Z = (const bf16_t*)(A.ws + WS_Z); bf16_t* MIX = (bf16_t*)(A.ws + WS_XN);
;     LAS float* ST = (LAS float*)(lds + 18432);
;     f32x4 acc[2] = {{0.f, 0.f, 0.f, 0.f}, {0.f, 0.f, 0.f, 0.f}};
;     ...
;     bf16x8 p0[2][2], p1[2][2]; f32x4 q0[2], q1[2];
;     bf16x8 r0_[2][2], r1_[2][2]; u32x2 ya0[2], ya1[2], zc0[2], zc1[2], zp0[2], zp1[2], zg0[2], zg1[2]; float bc0[2], bc1[2];
;     B_LOAD(p0, q0, 0); B_LOADY(r0_, ya0, zc0, zp0, zg0, bc0, 0);
; __global__ void __launch_bounds__(512, 2) hymba_fwd(Args A) {
;     ...
;             if (tid == 0) *s_item = (int)atomicAdd(ctl + CW_WORK + 1, 1u);
;             __syncthreads();
;             const int it = *s_item;
;             __syncthreads();
;             if (it >= N_PB) break;
;             chunkB_item(A, lds, tid, lane, wave, it);
.LBB0_275:
	s_or_b64 exec, exec, s[12:13]
	v_mov_b32_e32 v0, s34
	s_waitcnt lgkmcnt(0)
	s_barrier
	ds_read_b32 v0, v0
	s_movk_i32 s13, 0x7f
	s_mov_b64 s[14:15], -1
	s_waitcnt lgkmcnt(0)
	s_barrier
	v_cmp_lt_i32_e32 vcc, s13, v0
	v_readfirstlane_b32 s12, v0
	s_cbranch_vccnz .LBB0_270
	s_lshr_b32 s98, s12, 3
	s_mul_i32 s98, s98, 0xe00000
	s_add_u32 s98, s94, s98
	s_addc_u32 s99, s95, 0
	s_sub_u32 s98, s98, 0x1c00
	s_subb_u32 s99, s99, 0
	v_lshrrev_b32_e32 v240, 4, v144
	v_lshrrev_b32_e32 v241, 6, v144
	v_lshl_add_u32 v240, v241, 2, v240
	v_and_b32_e32 v241, 15, v144
	v_mul_u32_u24_e32 v242, 0x90, v240
	v_lshl_add_u32 v242, v241, 3, v242
	v_add_u32_e32 v242, 0x6000, v242
	v_mul_u32_u24_e32 v240, 0x1c00, v240
	v_lshl_add_u32 v240, v241, 3, v240
	s_and_b32 s22, s12, 7
	s_lshl_b32 s22, s22, 7
	s_add_i32 s22, s22, 0x800
	v_add_u32_e32 v240, s22, v240
	v_add_u32_e32 v240, 0x1c00, v240
	v_add_u32_e32 v241, 0x7000, v240
	v_mul_u32_u24_e32 v243, 0x90, v96
	v_lshl_add_u32 v243, v92, 1, v243
	v_add_u32_e32 v243, 0x6000, v243
	global_load_dwordx2 v[182:183], v240, s[98:99]
	global_load_dwordx2 v[188:189], v241, s[98:99]
	global_load_dwordx2 v[184:185], v240, s[98:99] offset:1280
	global_load_dwordx2 v[190:191], v241, s[98:99] offset:1280
	s_and_b32 s38, s12, 7
	v_mov_b32_e32 v244, s38
	v_lshl_add_u32 v244, v244, 6, v92
	v_lshlrev_b32_e32 v244, 2, v244
	v_readlane_b32 s20, v249, 10
	v_readlane_b32 s21, v249, 11
	v_readlane_b32 s22, v249, 12
	v_readlane_b32 s23, v249, 13
	s_nop 4
	global_load_dwordx4 v[228:231], v244, s[20:21]
	global_load_dwordx4 v[250:253], v244, s[22:23]
	global_load_dwordx2 v[232:233], v244, s[6:7]
	global_load_dwordx2 v[254:255], v244, s[6:7] offset:8
	s_ashr_i32 s13, s12, 31
	s_mul_i32 s14, s12, 0xc0000
	s_mul_hi_i32 s15, s12, 0xc0000
	s_add_u32 s14, s86, s14
	s_addc_u32 s15, s87, s15
	s_add_u32 s16, s14, 0x2000
	v_lshlrev_b32_e32 v94, 8, v91
	v_lshl_add_u32 v94, v132, 4, v94
	v_add_u32_e32 v234, v94, v124
	v_add_u32_e32 v235, v94, v126
	v_lshrrev_b32_e32 v236, 7, v144
	v_lshlrev_b32_e32 v236, 12, v236
	v_bfe_u32 v237, v144, 6, 1
	v_lshl_add_u32 v236, v237, 11, v236
	v_and_b32_e32 v237, 63, v144
	v_lshl_add_u32 v236, v237, 4, v236
	v_add_u32_e32 v236, 0x2000, v236
	v_add_u32_e32 v237, 0x400, v236
	v_add_u32_e32 v238, v148, v124
	v_add_u32_e32 v238, 0x2000, v238
	v_add_u32_e32 v239, v148, v126
	v_add_u32_e32 v239, 0x2000, v239
	v_mul_u32_u24_e32 v245, 0x1c00, v96
	v_lshl_add_u32 v245, v92, 1, v245
	v_mov_b32_e32 v246, s38
	v_lshl_add_u32 v245, v246, 7, v245
	v_add_u32_e32 v245, 0x800, v245
	v_lshlrev_b32_e32 v246, 4, v144
	v_bfe_u32 v247, v144, 6, 1
	v_lshlrev_b32_e32 v247, 12, v247
	v_and_b32_e32 v156, 63, v144
	v_lshl_add_u32 v247, v156, 4, v247
	global_load_dwordx4 v[210:213], v236, s[14:15]
	global_load_dwordx4 v[40:43], v237, s[14:15]
	global_load_dwordx4 v[0:3], v246, s[14:15]
	s_addc_u32 s17, s15, 0
	v_lshl_add_u64 v[8:9], s[14:15], 0, v[94:95]
	v_mov_b32_e32 v125, v95
	v_mov_b32_e32 v127, v95
	v_lshl_add_u64 v[4:5], v[8:9], 0, v[124:125]
	v_lshl_add_u64 v[10:11], v[98:99], 2, s[16:17]
	v_lshl_add_u64 v[12:13], v[100:101], 2, s[16:17]
	v_lshl_add_u64 v[14:15], v[102:103], 2, s[16:17]
	v_lshl_add_u64 v[8:9], v[8:9], 0, v[126:127]
	s_nop 0
	v_lshl_add_u64 v[16:17], v[104:105], 2, s[16:17]
	v_lshl_add_u64 v[8:9], v[108:109], 2, s[16:17]
	v_lshl_add_u64 v[10:11], v[110:111], 2, s[16:17]
	v_lshl_add_u64 v[12:13], v[112:113], 2, s[16:17]
	v_lshl_add_u64 v[14:15], v[114:115], 2, s[16:17]
	s_ashr_i32 s14, s12, 3
	s_lshl_b64 s[16:17], s[12:13], 19
	s_add_u32 s18, s3, s16
	s_addc_u32 s19, s11, s17
	v_mov_b32_e32 v149, v95
	v_lshl_add_u64 v[8:9], s[18:19], 0, v[148:149]
	s_ashr_i32 s15, s14, 31
	v_lshl_add_u64 v[16:17], s[18:19], 0, v[94:95]
	v_lshl_add_u64 v[18:19], v[8:9], 0, s[8:9]
	s_lshl_b64 s[16:17], s[14:15], 11
	v_lshl_add_u64 v[12:13], v[16:17], 0, v[124:125]
	v_lshl_add_u64 v[24:25], v[18:19], 0, v[124:125]
	global_load_dwordx4 v[8:11], v246, s[18:19]
	s_nop 0
	v_or_b32_e32 v27, s16, v96
	global_load_dwordx2 v[196:197], v[24:25], off
	v_mov_b64_e32 v[24:25], s[94:95]
	v_lshl_add_u32 v26, s38, 6, v92
	v_mad_u64_u32 v[24:25], s[18:19], v27, s35, v[24:25]
	v_mad_i32_i24 v25, s17, v147, v25
	v_lshlrev_b32_e32 v150, 1, v26
	v_mov_b32_e32 v151, v95
	v_lshl_add_u64 v[24:25], v[24:25], 0, v[150:151]
	global_load_dwordx2 v[174:175], v[24:25], off offset:2048
	v_mov_b32_e32 v170, v95
	v_mov_b32_e32 v171, v95
	s_and_saveexec_b64 s[18:19], s[4:5]
	s_cbranch_execz .LBB0_278
	v_add_co_u32_e32 v28, vcc, 0xfffff000, v24
	s_nop 1
	v_addc_co_u32_e32 v29, vcc, -1, v25, vcc
	global_load_dwordx2 v[170:171], v[28:29], off offset:-1024
.LBB0_278:
	s_or_b64 exec, exec, s[18:19]
	s_lshl_b64 s[18:19], s[12:13], 13
	s_add_u32 s18, s24, s18
	v_lshl_add_u64 v[16:17], v[16:17], 0, v[126:127]
	s_addc_u32 s19, s25, s19
	v_lshlrev_b32_e32 v214, 2, v96
	global_load_dwordx2 v[176:177], v[24:25], off offset:3328
	global_load_dword v172, v214, s[18:19]
	v_or_b32_e32 v24, s16, v106
	v_lshl_add_u64 v[16:17], v[18:19], 0, v[126:127]
	v_mov_b64_e32 v[18:19], s[94:95]
	v_mad_u64_u32 v[18:19], s[20:21], v24, s35, v[18:19]
	v_mad_i32_i24 v19, s17, v147, v19
	v_lshl_add_u64 v[18:19], v[18:19], 0, v[150:151]
	v_add_co_u32_e32 v24, vcc, s36, v18
	v_lshlrev_b32_e32 v215, 2, v106
	s_nop 0
	v_addc_co_u32_e32 v25, vcc, -1, v19, vcc
	global_load_dwordx2 v[194:195], v[16:17], off
	global_load_dwordx2 v[168:169], v[18:19], off offset:2048
	global_load_dwordx2 v[164:165], v[24:25], off offset:-1024
	global_load_dwordx2 v[166:167], v[18:19], off offset:3328
	global_load_dword v162, v215, s[18:19]
	v_readlane_b32 s20, v249, 10
	v_lshlrev_b32_e32 v16, 2, v26
	v_mov_b32_e32 v17, v95
	v_readlane_b32 s21, v249, 11
	v_readlane_b32 s22, v249, 12
	v_readlane_b32 s23, v249, 13
	v_lshl_add_u64 v[152:153], s[20:21], 0, v[16:17]
	s_lshl_b64 s[20:21], s[14:15], 22
	v_lshl_add_u64 v[154:155], s[22:23], 0, v[16:17]
	v_lshl_add_u64 v[156:157], s[6:7], 0, v[16:17]
	v_lshl_add_u64 v[16:17], s[20:21], 0, v[150:151]
	v_lshl_add_u64 v[158:159], v[116:117], 0, v[16:17]
	v_lshl_add_u64 v[160:161], v[118:119], 0, v[16:17]
	v_mov_b32_e32 v16, 0
	s_mov_b32 s39, 1
	s_lshl_b64 s[18:19], s[12:13], 5
	s_mov_b64 s[20:21], 0
	v_mov_b32_e32 v17, v16
	v_mov_b32_e32 v18, v16
	v_mov_b32_e32 v19, v16
	v_mov_b32_e32 v32, v16
	v_mov_b32_e32 v33, v16
	v_mov_b32_e32 v34, v16
	v_mov_b32_e32 v35, v16
	s_branch .LBB0_280
; __device__ __forceinline__ void chunkB_item(const Args& A, LAS unsigned char* lds, int tid, int lane, int wave, int bh) {
;     ...
;     bf16x8 p0[2][2], p1[2][2]; f32x4 q0[2], q1[2];
;     bf16x8 r0_[2][2], r1_[2][2]; u32x2 ya0[2], ya1[2], zc0[2], zc1[2], zp0[2], zp1[2], zg0[2], zg1[2]; float bc0[2], bc1[2];
;     B_LOAD(p0, q0, 0); B_LOADY(r0_, ya0, zc0, zp0, zg0, bc0, 0);
; #pragma unroll 1
;     for (int c = 0; c < 32; ++c) {
;         const int cn = c + 1 < 32 ? c + 1 : 31;
;         B_LOAD(p1, q1, cn); B_LOADY(r1_, ya1, zc1, zp1, zg1, bc1, cn);
;         B_STEP(p0, q0, r0_, ya0, zc0, zp0, zg0, bc0, c);
; #pragma unroll
;         for (int nn = 0; nn < 2; ++nn) { p0[nn][0] = p1[nn][0]; p0[nn][1] = p1[nn][1]; q0[nn] = q1[nn]; r0_[nn][0] = r1_[nn][0]; r0_[nn][1] = r1_[nn][1];
;             ya0[nn] = ya1[nn]; zc0[nn] = zc1[nn]; zp0[nn] = zp1[nn]; zg0[nn] = zg1[nn]; bc0[nn] = bc1[nn]; }
.LBB0_279:
	s_or_b64 exec, exec, s[22:23]
	s_waitcnt lgkmcnt(0)
	s_barrier
	v_mov_b32_dpp v170, v174 row_shr:1 row_mask:0xf bank_mask:0xf
	v_mov_b32_dpp v171, v175 row_shr:1 row_mask:0xf bank_mask:0xf
	v_mov_b32_dpp v164, v174 row_ror:1 row_mask:0xf bank_mask:0xf
	v_mov_b32_dpp v165, v175 row_ror:1 row_mask:0xf bank_mask:0xf
	v_mov_b32_dpp v164, v168 row_shr:1 row_mask:0xf bank_mask:0xf
	v_mov_b32_dpp v165, v169 row_shr:1 row_mask:0xf bank_mask:0xf
	ds_read2st64_b64 v[20:23], v141 offset0:36 offset1:37
	s_waitcnt lgkmcnt(1)
	ds_read2st64_b64 v[36:39], v141 offset0:38 offset1:39
	v_lshlrev_b32_e32 v42, 16, v176
	v_and_b32_e32 v43, 0xffff0000, v176
	v_lshlrev_b32_e32 v40, 16, v174
	s_waitcnt lgkmcnt(1)
	v_pk_add_f32 v[20:21], v[20:21], 0 op_sel_hi:[1,0]
	v_and_b32_e32 v41, 0xffff0000, v174
	v_pk_add_f32 v[20:21], v[20:21], v[22:23]
	v_mul_f32_e32 v23, 0xbfb8aa3b, v42
	s_waitcnt lgkmcnt(0)
	v_pk_add_f32 v[20:21], v[20:21], v[36:37]
	v_exp_f32_e32 v23, v23
	v_pk_add_f32 v[20:21], v[20:21], v[38:39]
	v_lshlrev_b32_e32 v36, 16, v170
	v_pk_mul_f32 v[20:21], v[20:21], s[10:11] op_sel_hi:[1,0]
	v_add_f32_e32 v23, 1.0, v23
	v_fma_f32 v22, -v20, v20, v21
	v_max_f32_e32 v22, 0, v22
	v_add_f32_e32 v22, 0x3a27c5ac, v22
	v_rcp_f32_e32 v38, v23
	v_mul_f32_e32 v23, 0xbfb8aa3b, v43
	v_rsq_f32_e32 v22, v22
	v_exp_f32_e32 v23, v23
	v_and_b32_e32 v37, 0xffff0000, v170
	v_pk_add_f32 v[56:57], v[198:199], v[20:21] op_sel_hi:[1,0] neg_lo:[0,1] neg_hi:[0,1]
	v_pk_add_f32 v[36:37], v[36:37], v[40:41] neg_lo:[0,1] neg_hi:[0,1]
	v_pk_mul_f32 v[56:57], v[56:57], v[22:23] op_sel_hi:[1,0]
	v_add_f32_e32 v23, 1.0, v23
	s_waitcnt vmcnt(11)
	v_pk_fma_f32 v[36:37], v[36:37], v[232:233], v[40:41]
	v_lshlrev_b32_e32 v40, 16, v177
	v_rcp_f32_e32 v39, v23
	v_mul_f32_e32 v23, 0xbfb8aa3b, v40
	v_exp_f32_e32 v23, v23
	v_pk_fma_f32 v[56:57], v[228:229], v[56:57], v[250:251]
	v_and_b32_e32 v41, 0xffff0000, v177
	v_pk_fma_f32 v[36:37], v[172:173], v[36:37], v[56:57] op_sel_hi:[0,1,1]
	v_add_f32_e32 v23, 1.0, v23
	v_rcp_f32_e32 v56, v23
	global_load_dwordx2 v[178:179], v238, s[100:101]
	v_mul_f32_e32 v23, 0xbfb8aa3b, v41
	v_exp_f32_e32 v23, v23
	v_pk_add_f32 v[20:21], v[196:197], v[20:21] op_sel_hi:[1,0] neg_lo:[0,1] neg_hi:[0,1]
	v_pk_mul_f32 v[38:39], v[38:39], v[42:43]
	v_lshlrev_b32_e32 v42, 16, v171
	v_pk_mul_f32 v[20:21], v[20:21], v[22:23] op_sel_hi:[1,0]
	v_add_f32_e32 v22, 1.0, v23
	v_rcp_f32_e32 v57, v22
	v_pk_mul_f32 v[36:37], v[38:39], v[36:37]
	global_load_dwordx2 v[180:181], v239, s[100:101]
	v_lshlrev_b32_e32 v38, 16, v175
	v_and_b32_e32 v39, 0xffff0000, v175
	v_and_b32_e32 v43, 0xffff0000, v171
	v_pk_add_f32 v[22:23], v[42:43], v[38:39] neg_lo:[0,1] neg_hi:[0,1]
	v_pk_fma_f32 v[20:21], v[230:231], v[20:21], v[252:253]
	v_pk_fma_f32 v[22:23], v[22:23], v[254:255], v[38:39]
	v_lshl_add_u64 v[42:43], v[160:161], 0, s[20:21]
	v_pk_fma_f32 v[20:21], v[172:173], v[22:23], v[20:21] op_sel_hi:[0,1,1]
	v_pk_mul_f32 v[22:23], v[56:57], v[40:41]
	v_cvt_pk_bf16_f32 v40, v36, v37
	v_pk_mul_f32 v[38:39], v[22:23], v[20:21]
	ds_read2st64_b64 v[20:23], v143 offset0:36 offset1:37
	v_cvt_pk_bf16_f32 v41, v38, v39
	ds_read2st64_b64 v[36:39], v143 offset0:38 offset1:39
	global_store_dwordx2 v[42:43], v[40:41], off
	v_lshlrev_b32_e32 v40, 16, v164
	s_waitcnt lgkmcnt(1)
	v_pk_add_f32 v[20:21], v[20:21], 0 op_sel_hi:[1,0]
	v_and_b32_e32 v41, 0xffff0000, v164
	v_pk_add_f32 v[20:21], v[20:21], v[22:23]
	s_waitcnt lgkmcnt(0)
	v_pk_add_f32 v[20:21], v[20:21], v[36:37]
	v_lshlrev_b32_e32 v36, 16, v168
	v_pk_add_f32 v[20:21], v[20:21], v[38:39]
	v_lshlrev_b32_e32 v38, 16, v166
	v_mul_f32_e32 v23, 0xbfb8aa3b, v38
	v_exp_f32_e32 v23, v23
	v_pk_mul_f32 v[20:21], v[20:21], s[10:11] op_sel_hi:[1,0]
	v_and_b32_e32 v39, 0xffff0000, v166
	v_fma_f32 v22, -v20, v20, v21
	v_max_f32_e32 v22, 0, v22
	v_add_f32_e32 v23, 1.0, v23
	v_add_f32_e32 v22, 0x3a27c5ac, v22
	v_rcp_f32_e32 v42, v23
	v_mul_f32_e32 v23, 0xbfb8aa3b, v39
	v_rsq_f32_e32 v22, v22
	v_exp_f32_e32 v23, v23
	v_and_b32_e32 v37, 0xffff0000, v168
	v_pk_add_f32 v[54:55], v[54:55], v[20:21] op_sel_hi:[1,0] neg_lo:[0,1] neg_hi:[0,1]
	v_pk_add_f32 v[40:41], v[40:41], v[36:37] neg_lo:[0,1] neg_hi:[0,1]
	v_pk_mul_f32 v[54:55], v[54:55], v[22:23] op_sel_hi:[1,0]
	v_add_f32_e32 v23, 1.0, v23
	v_pk_fma_f32 v[36:37], v[40:41], v[232:233], v[36:37]
	v_lshlrev_b32_e32 v40, 16, v167
	v_rcp_f32_e32 v43, v23
	v_mul_f32_e32 v23, 0xbfb8aa3b, v40
	v_exp_f32_e32 v23, v23
	v_pk_fma_f32 v[54:55], v[228:229], v[54:55], v[250:251]
	v_and_b32_e32 v41, 0xffff0000, v167
	v_pk_fma_f32 v[36:37], v[162:163], v[36:37], v[54:55] op_sel_hi:[0,1,1]
	v_add_f32_e32 v23, 1.0, v23
	v_rcp_f32_e32 v54, v23
	v_mul_f32_e32 v23, 0xbfb8aa3b, v41
	v_exp_f32_e32 v23, v23
	v_pk_add_f32 v[20:21], v[52:53], v[20:21] op_sel_hi:[1,0] neg_lo:[0,1] neg_hi:[0,1]
	v_pk_mul_f32 v[38:39], v[42:43], v[38:39]
	v_lshlrev_b32_e32 v42, 16, v165
	v_pk_mul_f32 v[20:21], v[20:21], v[22:23] op_sel_hi:[1,0]
	v_add_f32_e32 v22, 1.0, v23
	v_rcp_f32_e32 v55, v22
	v_pk_mul_f32 v[36:37], v[38:39], v[36:37]
	v_lshlrev_b32_e32 v38, 16, v169
	v_and_b32_e32 v39, 0xffff0000, v169
	v_and_b32_e32 v43, 0xffff0000, v165
	v_pk_add_f32 v[22:23], v[42:43], v[38:39] neg_lo:[0,1] neg_hi:[0,1]
	v_pk_fma_f32 v[20:21], v[230:231], v[20:21], v[252:253]
	v_pk_fma_f32 v[22:23], v[22:23], v[254:255], v[38:39]
	v_pk_fma_f32 v[20:21], v[162:163], v[22:23], v[20:21] op_sel_hi:[0,1,1]
	v_pk_mul_f32 v[22:23], v[54:55], v[40:41]
	v_pk_mul_f32 v[20:21], v[22:23], v[20:21]
	v_cvt_pk_bf16_f32 v22, v36, v37
	v_cvt_pk_bf16_f32 v23, v20, v21
	v_lshl_add_u64 v[20:21], v[158:159], 0, s[20:21]
	s_add_u32 s20, s20, 0x20000
	global_store_dwordx2 v[20:21], v[22:23], off
	s_addc_u32 s21, s21, 0
	s_add_i32 s39, s39, 1
	s_waitcnt vmcnt(2)
	v_mov_b64_e32 v[164:165], v[192:193]
	s_cmp_eq_u32 s20, 0x400000
	v_mov_b64_e32 v[170:171], v[186:187]
	v_mov_b64_e32 v[166:167], v[190:191]
	v_mov_b64_e32 v[176:177], v[184:185]
	v_mov_b64_e32 v[174:175], v[182:183]
	v_mov_b64_e32 v[168:169], v[188:189]
	v_mov_b32_e32 v162, v127
	v_mov_b32_e32 v172, v125
	v_mov_b32_e32 v40, v216
	v_mov_b32_e32 v41, v217
	v_mov_b32_e32 v42, v218
	v_mov_b32_e32 v43, v219
	v_mov_b32_e32 v196, v178
	v_mov_b32_e32 v197, v179
	v_mov_b32_e32 v194, v180
	v_mov_b32_e32 v195, v181
	s_cbranch_scc1 .LBB0_268
.LBB0_280:
	s_cmp_lg_u32 s20, 0x3e0000
	s_cselect_b32 s15, s39, 31
	s_add_u32 s22, s18, s15
	s_addc_u32 s23, s19, 0
	s_mul_i32 s40, s23, 0x6000
	s_mul_hi_u32 s41, s22, 0x6000
	s_add_i32 s41, s41, s40
	s_mul_i32 s40, s22, 0x6000
	s_add_u32 s40, s86, s40
	s_addc_u32 s41, s87, s41
	s_waitcnt vmcnt(10)
	ds_write_b128 v246, v[0:3] offset:43008
	ds_write_b128 v246, v[8:11] offset:51200
	ds_write_b64 v242, v[182:183]
	ds_write_b64 v242, v[188:189] offset:576
	ds_write_b64 v242, v[184:185] offset:9216
	ds_write_b64 v242, v[190:191] offset:9792
	s_lshl_b64 s[100:101], s[22:23], 14
	s_add_u32 s100, s3, s100
	s_addc_u32 s101, s11, s101
	s_lshl_b64 s[22:23], s[22:23], 8
	s_add_u32 s22, s24, s22
	s_addc_u32 s23, s25, s23
	s_lshl_b32 s15, s15, 6
	s_waitcnt vmcnt(10)
	s_add_u32 s15, s16, s15
	v_mov_b32_e32 v76, v210
	v_mov_b32_e32 v77, v211
	v_mov_b32_e32 v78, v212
	v_mov_b32_e32 v79, v213
	s_sub_u32 s98, s15, 1
	s_mul_i32 s98, s98, 0x1c00
	s_add_u32 s98, s98, s94
	s_addc_u32 s99, s95, 0
	s_mov_b32 vcc_lo, 0x10001
	s_mov_b32 vcc_hi, 0x10001
	global_load_dwordx2 v[182:183], v240, s[98:99]
	global_load_dwordx2 v[188:189], v241, s[98:99]
	global_load_dwordx2 v[184:185], v240, s[98:99] offset:1280
	global_load_dwordx2 v[190:191], v241, s[98:99] offset:1280
	s_mov_b64 exec, vcc
	global_load_dwordx2 v[186:187], v245, s[98:99]
	s_mov_b64 exec, -1
	global_load_dword v125, v214, s[22:23]
	global_load_dword v127, v215, s[22:23]
	v_cvt_pk_bf16_f32 v80, v16, 0
	v_lshlrev_b32_e32 v81, 16, v80
	v_sub_f32_e32 v16, v16, v81
	v_cvt_pk_bf16_f32 v16, v16, s0
	ds_write_b16 v107, v80
	ds_write_b16 v107, v16 offset:9216
	v_cvt_pk_bf16_f32 v16, v17, 0
	v_lshlrev_b32_e32 v80, 16, v16
	v_sub_f32_e32 v17, v17, v80
	v_cvt_pk_bf16_f32 v17, v17, s0
	ds_write_b16 v107, v16 offset:144
	ds_write_b16 v107, v17 offset:9360
	v_cvt_pk_bf16_f32 v16, v18, 0
	v_lshlrev_b32_e32 v17, 16, v16
	v_sub_f32_e32 v17, v18, v17
	v_cvt_pk_bf16_f32 v17, v17, s0
	ds_write_b16 v107, v16 offset:288
	ds_write_b16 v107, v17 offset:9504
	v_cvt_pk_bf16_f32 v16, v19, 0
	v_lshlrev_b32_e32 v17, 16, v16
	v_sub_f32_e32 v17, v19, v17
	v_cvt_pk_bf16_f32 v17, v17, s0
	ds_write_b16 v107, v16 offset:432
	ds_write_b16 v107, v17 offset:9648
	v_cvt_pk_bf16_f32 v16, v32, 0
	v_lshlrev_b32_e32 v17, 16, v16
	v_sub_f32_e32 v17, v32, v17
	v_cvt_pk_bf16_f32 v17, v17, s0
	ds_write_b16 v135, v16
	ds_write_b16 v135, v17 offset:9216
	v_cvt_pk_bf16_f32 v16, v33, 0
	v_lshlrev_b32_e32 v17, 16, v16
	v_sub_f32_e32 v17, v33, v17
	v_cvt_pk_bf16_f32 v17, v17, s0
	ds_write_b16 v135, v16 offset:144
	ds_write_b16 v135, v17 offset:9360
	v_cvt_pk_bf16_f32 v16, v34, 0
	v_lshlrev_b32_e32 v17, 16, v16
	v_sub_f32_e32 v17, v34, v17
	v_cvt_pk_bf16_f32 v17, v17, s0
	ds_write_b16 v135, v16 offset:288
	ds_write_b16 v135, v17 offset:9504
	v_cvt_pk_bf16_f32 v16, v35, 0
	v_lshlrev_b32_e32 v17, 16, v16
	v_sub_f32_e32 v17, v35, v17
	v_cvt_pk_bf16_f32 v17, v17, s0
	ds_write_b16 v135, v16 offset:432
	ds_write_b16 v135, v17 offset:9648
	s_waitcnt lgkmcnt(0)
	s_barrier
	ds_read_b128 v[198:201], v247 offset:43008
	ds_read_b128 v[224:227], v247 offset:51200
	ds_read_b128 v[72:75], v247 offset:44032
	ds_read_b128 v[220:223], v247 offset:52224
	ds_read_b128 v[36:39], v247 offset:45056
	ds_read_b128 v[20:23], v247 offset:46080
	ds_read_b128 v[56:59], v247 offset:53248
	ds_read_b128 v[52:55], v247 offset:54272
	ds_read_b128 v[80:83], v139
	ds_read_b128 v[32:35], v139 offset:64
	s_waitcnt lgkmcnt(1)
	v_mfma_f32_16x16x32_bf16 v[16:19], v[80:83], v[198:201], v[76:79]
	ds_read_b128 v[84:87], v139 offset:9216
	s_nop 1
	ds_read_b128 v[76:79], v139 offset:9280
	s_waitcnt vmcnt(7)
	v_lshlrev_b32_e32 v202, 16, v196
	v_and_b32_e32 v203, 0xffff0000, v196
	s_waitcnt lgkmcnt(1)
	v_mfma_f32_16x16x32_bf16 v[16:19], v[84:87], v[198:201], v[16:19]
	v_lshlrev_b32_e32 v196, 16, v197
	v_and_b32_e32 v197, 0xffff0000, v197
	v_and_b32_e32 v151, 64, v209
	v_mfma_f32_16x16x32_bf16 v[198:201], v[80:83], v[224:227], 0
	v_xor_b32_e32 v149, 16, v209
	v_add_u32_e32 v151, 64, v151
	v_cmp_lt_i32_e32 vcc, v149, v151
	v_mfma_f32_16x16x32_bf16 v[198:201], v[32:35], v[220:223], v[198:201]
	v_xor_b32_e32 v224, 32, v209
	v_cndmask_b32_e32 v149, v209, v149, vcc
	v_lshlrev_b32_e32 v149, 2, v149
	v_cmp_lt_i32_e32 vcc, v224, v151
	v_mfma_f32_16x16x32_bf16 v[16:19], v[32:35], v[72:75], v[16:19]
	global_load_dwordx4 v[0:3], v246, s[40:41]
	s_nop 2
	v_add_f32_e64 v198, v198, v202
	v_add_f32_e64 v199, v199, v203
	v_pk_add_f32 v[196:197], v[200:201], v[196:197]
	v_pk_mul_f32 v[200:201], v[198:199], v[198:199]
	v_pk_mul_f32 v[202:203], v[196:197], v[196:197]
	global_load_dwordx4 v[8:11], v246, s[100:101]
	v_mov_b32_e32 v220, v198
	v_mov_b32_e32 v221, v200
	v_mov_b32_e32 v200, v199
	v_pk_add_f32 v[200:201], v[220:221], v[200:201]
	v_mov_b32_e32 v220, v196
	v_mov_b32_e32 v221, v202
	v_mov_b32_e32 v202, v197
	v_pk_add_f32 v[202:203], v[220:221], v[202:203]
	v_cndmask_b32_e32 v151, v209, v224, vcc
	global_load_dwordx4 v[210:213], v236, s[40:41]
	v_pk_add_f32 v[200:201], v[200:201], v[202:203]
	ds_bpermute_b32 v202, v149, v200
	ds_bpermute_b32 v203, v149, v201
	v_lshlrev_b32_e32 v151, 2, v151
	global_load_dwordx4 v[216:219], v237, s[40:41]
	s_waitcnt lgkmcnt(2)
	v_mfma_f32_16x16x32_bf16 v[16:19], v[76:79], v[72:75], v[16:19]
	s_waitcnt lgkmcnt(0)
	v_pk_add_f32 v[200:201], v[200:201], v[202:203]
	ds_bpermute_b32 v202, v151, v200
	ds_bpermute_b32 v203, v151, v201
	s_and_saveexec_b64 s[22:23], s[30:31]
	s_cbranch_execz .LBB0_282
	s_waitcnt lgkmcnt(0)
	v_pk_add_f32 v[72:73], v[200:201], v[202:203]
	v_add_u32_e32 v74, s26, v130
	ds_write_b64 v74, v[72:73] offset:18432
.LBB0_282:
	s_or_b64 exec, exec, s[22:23]
	s_waitcnt vmcnt(11)
	v_mfma_f32_16x16x32_bf16 v[56:59], v[80:83], v[56:59], 0
	s_waitcnt vmcnt(11)
	v_lshlrev_b32_e32 v72, 16, v194
	v_and_b32_e32 v73, 0xffff0000, v194
	v_lshlrev_b32_e32 v74, 16, v195
	v_mfma_f32_16x16x32_bf16 v[54:57], v[32:35], v[52:55], v[56:59]
	v_and_b32_e32 v75, 0xffff0000, v195
	v_mfma_f32_16x16x32_bf16 v[40:43], v[80:83], v[36:39], v[40:43]
	v_mfma_f32_16x16x32_bf16 v[36:39], v[84:87], v[36:39], v[40:43]
	s_nop 4
	v_add_f32_e64 v54, v54, v72
	v_add_f32_e64 v55, v55, v73
	v_pk_add_f32 v[52:53], v[56:57], v[74:75]
	v_pk_mul_f32 v[56:57], v[54:55], v[54:55]
	v_pk_mul_f32 v[58:59], v[52:53], v[52:53]
	v_mov_b32_e32 v72, v54
	v_mov_b32_e32 v73, v56
	v_mov_b32_e32 v56, v55
	v_mov_b32_e32 v42, v52
	v_mov_b32_e32 v43, v58
	v_mov_b32_e32 v58, v53
	v_pk_add_f32 v[40:41], v[72:73], v[56:57]
	v_pk_add_f32 v[42:43], v[42:43], v[58:59]
	v_mfma_f32_16x16x32_bf16 v[32:35], v[32:35], v[20:23], v[36:39]
	v_add_f32_e64 v40, v40, v42
	v_add_f32_e64 v41, v41, v43
	ds_bpermute_b32 v42, v149, v40
	ds_bpermute_b32 v43, v149, v41
	v_mfma_f32_16x16x32_bf16 v[32:35], v[76:79], v[20:23], v[32:35]
	s_waitcnt lgkmcnt(0)
	v_pk_add_f32 v[36:37], v[40:41], v[42:43]
	ds_bpermute_b32 v38, v151, v36
	ds_bpermute_b32 v39, v151, v37
	ds_read_b64 v[174:175], v243
	ds_read_b64 v[168:169], v243 offset:2304
	ds_read_b64 v[176:177], v243 offset:9216
	ds_read_b64 v[166:167], v243 offset:11520
	s_and_saveexec_b64 s[22:23], s[30:31]
	s_cbranch_execz .LBB0_279
	s_waitcnt lgkmcnt(0)
	v_pk_add_f32 v[20:21], v[36:37], v[38:39]
	v_add_u32_e32 v22, s27, v130
	ds_write_b64 v22, v[20:21] offset:18432
	s_branch .LBB0_279
